# grid barrier: non-leader workgroups poll the top-level release word directly instead of waiting for their XCD leader's relay
# speedup vs baseline: 1.0122x; 1.0012x over previous
.LBB0_194:
	s_or_b64 exec, exec, s[28:29]
	v_cvt_f32_u32_e32 v5, v3
	s_waitcnt vmcnt(0)
	v_readfirstlane_b32 s19, v4
	v_sub_u32_e32 v4, 0, v3
	v_rcp_iflag_f32_e32 v5, v5
	v_add_u32_e32 v6, s19, v1
	v_mul_f32_e32 v5, 0x4f7ffffe, v5
	v_cvt_u32_f32_e32 v5, v5
	v_mul_lo_u32 v1, v4, v5
	v_mul_hi_u32 v1, v5, v1
	v_add_u32_e32 v1, v5, v1
	v_mul_hi_u32 v1, v6, v1
	v_mul_lo_u32 v4, v1, v3
	v_sub_u32_e32 v4, v6, v4
	v_add_u32_e32 v5, 1, v1
	v_cmp_ge_u32_e32 vcc, v4, v3
	s_nop 1
	v_cndmask_b32_e32 v1, v1, v5, vcc
	v_sub_u32_e32 v5, v4, v3
	v_cndmask_b32_e32 v4, v4, v5, vcc
	v_add_u32_e32 v5, 1, v1
	v_cmp_ge_u32_e32 vcc, v4, v3
	v_add_u32_e32 v4, 1, v6
	s_nop 0
	v_cndmask_b32_e32 v1, v1, v5, vcc
	v_mul_lo_u32 v5, v3, v1
	v_add_u32_e32 v3, v5, v3
	v_cmp_ne_u32_e32 vcc, v4, v3
	s_and_saveexec_b64 s[28:29], vcc
	s_xor_b64 s[28:29], exec, s[28:29]
	s_cbranch_execz .LBB0_208
	s_waitcnt lgkmcnt(0)
	global_load_dword v0, v2, s[94:95] sc1
	s_waitcnt vmcnt(0)
	v_cmp_eq_u32_e32 vcc, v0, v1
	s_and_saveexec_b64 s[34:35], vcc
	s_cbranch_execz .LBB0_207
	s_mov_b32 s19, 1
	s_mov_b64 s[38:39], 0
	s_branch .LBB0_198

.LBB0_202:
	global_load_dword v0, v2, s[94:95] sc1
	s_add_i32 s19, s19, 1
	s_mov_b64 s[44:45], -1
	s_waitcnt vmcnt(0)
	v_cmp_ne_u32_e32 vcc, v0, v1
	s_orn2_b64 s[42:43], vcc, exec
	s_branch .LBB0_197

.LBB0_365:
	s_or_b64 exec, exec, s[26:27]
	v_cvt_f32_u32_e32 v5, v3
	s_waitcnt vmcnt(0)
	v_readfirstlane_b32 s2, v4
	v_sub_u32_e32 v4, 0, v3
	v_rcp_iflag_f32_e32 v5, v5
	v_add_u32_e32 v6, s2, v1
	v_mul_f32_e32 v5, 0x4f7ffffe, v5
	v_cvt_u32_f32_e32 v5, v5
	v_mul_lo_u32 v1, v4, v5
	v_mul_hi_u32 v1, v5, v1
	v_add_u32_e32 v1, v5, v1
	v_mul_hi_u32 v1, v6, v1
	v_mul_lo_u32 v4, v1, v3
	v_sub_u32_e32 v4, v6, v4
	v_add_u32_e32 v5, 1, v1
	v_cmp_ge_u32_e32 vcc, v4, v3
	s_nop 1
	v_cndmask_b32_e32 v1, v1, v5, vcc
	v_sub_u32_e32 v5, v4, v3
	v_cndmask_b32_e32 v4, v4, v5, vcc
	v_add_u32_e32 v5, 1, v1
	v_cmp_ge_u32_e32 vcc, v4, v3
	v_add_u32_e32 v4, 1, v6
	s_nop 0
	v_cndmask_b32_e32 v1, v1, v5, vcc
	v_mul_lo_u32 v5, v3, v1
	v_add_u32_e32 v3, v5, v3
	v_cmp_ne_u32_e32 vcc, v4, v3
	s_and_saveexec_b64 s[26:27], vcc
	s_xor_b64 s[26:27], exec, s[26:27]
	s_cbranch_execz .LBB0_379
	s_waitcnt lgkmcnt(0)
	global_load_dword v0, v2, s[94:95] sc1
	s_waitcnt vmcnt(0)
	v_cmp_eq_u32_e32 vcc, v0, v1
	s_and_saveexec_b64 s[28:29], vcc
	s_cbranch_execz .LBB0_378
	s_mov_b32 s2, 1
	s_mov_b64 s[34:35], 0
	s_branch .LBB0_369

.LBB0_373:
	global_load_dword v0, v2, s[94:95] sc1
	s_add_i32 s2, s2, 1
	s_mov_b64 s[42:43], -1
	s_waitcnt vmcnt(0)
	v_cmp_ne_u32_e32 vcc, v0, v1
	s_orn2_b64 s[40:41], vcc, exec
	s_branch .LBB0_368

.LBB0_509:
	s_or_b64 exec, exec, s[22:23]
	v_cvt_f32_u32_e32 v5, v3
	s_waitcnt vmcnt(0)
	v_readfirstlane_b32 s2, v4
	v_sub_u32_e32 v4, 0, v3
	v_rcp_iflag_f32_e32 v5, v5
	v_add_u32_e32 v6, s2, v1
	v_mul_f32_e32 v5, 0x4f7ffffe, v5
	v_cvt_u32_f32_e32 v5, v5
	v_mul_lo_u32 v1, v4, v5
	v_mul_hi_u32 v1, v5, v1
	v_add_u32_e32 v1, v5, v1
	v_mul_hi_u32 v1, v6, v1
	v_mul_lo_u32 v4, v1, v3
	v_sub_u32_e32 v4, v6, v4
	v_add_u32_e32 v5, 1, v1
	v_cmp_ge_u32_e32 vcc, v4, v3
	s_nop 1
	v_cndmask_b32_e32 v1, v1, v5, vcc
	v_sub_u32_e32 v5, v4, v3
	v_cndmask_b32_e32 v4, v4, v5, vcc
	v_add_u32_e32 v5, 1, v1
	v_cmp_ge_u32_e32 vcc, v4, v3
	v_add_u32_e32 v4, 1, v6
	s_nop 0
	v_cndmask_b32_e32 v1, v1, v5, vcc
	v_mul_lo_u32 v5, v3, v1
	v_add_u32_e32 v3, v5, v3
	v_cmp_ne_u32_e32 vcc, v4, v3
	s_and_saveexec_b64 s[22:23], vcc
	s_xor_b64 s[22:23], exec, s[22:23]
	s_cbranch_execz .LBB0_523
	s_waitcnt lgkmcnt(0)
	global_load_dword v0, v2, s[94:95] sc1
	s_waitcnt vmcnt(0)
	v_cmp_eq_u32_e32 vcc, v0, v1
	s_and_saveexec_b64 s[28:29], vcc
	s_cbranch_execz .LBB0_522
	s_mov_b32 s2, 1
	s_mov_b64 s[34:35], 0
	s_branch .LBB0_513

.LBB0_600:
	s_or_b64 exec, exec, s[20:21]
	v_cvt_f32_u32_e32 v5, v3
	s_waitcnt vmcnt(0)
	v_readfirstlane_b32 s2, v4
	v_sub_u32_e32 v4, 0, v3
	v_rcp_iflag_f32_e32 v5, v5
	v_add_u32_e32 v6, s2, v1
	v_mul_f32_e32 v5, 0x4f7ffffe, v5
	v_cvt_u32_f32_e32 v5, v5
	v_mul_lo_u32 v1, v4, v5
	v_mul_hi_u32 v1, v5, v1
	v_add_u32_e32 v1, v5, v1
	v_mul_hi_u32 v1, v6, v1
	v_mul_lo_u32 v4, v1, v3
	v_sub_u32_e32 v4, v6, v4
	v_add_u32_e32 v5, 1, v1
	v_cmp_ge_u32_e32 vcc, v4, v3
	s_nop 1
	v_cndmask_b32_e32 v1, v1, v5, vcc
	v_sub_u32_e32 v5, v4, v3
	v_cndmask_b32_e32 v4, v4, v5, vcc
	v_add_u32_e32 v5, 1, v1
	v_cmp_ge_u32_e32 vcc, v4, v3
	v_add_u32_e32 v4, 1, v6
	s_nop 0
	v_cndmask_b32_e32 v1, v1, v5, vcc
	v_mul_lo_u32 v5, v3, v1
	v_add_u32_e32 v3, v5, v3
	v_cmp_ne_u32_e32 vcc, v4, v3
	s_and_saveexec_b64 s[20:21], vcc
	s_xor_b64 s[20:21], exec, s[20:21]
	s_cbranch_execz .LBB0_614
	s_waitcnt lgkmcnt(0)
	global_load_dword v0, v2, s[94:95] sc1
	s_waitcnt vmcnt(0)
	v_cmp_eq_u32_e32 vcc, v0, v1
	s_and_saveexec_b64 s[22:23], vcc
	s_cbranch_execz .LBB0_613
	s_mov_b32 s2, 1
	s_mov_b64 s[24:25], 0
	s_branch .LBB0_604

.LBB0_608:
	global_load_dword v0, v2, s[94:95] sc1
	s_add_i32 s2, s2, 1
	s_mov_b64 s[34:35], -1
	s_waitcnt vmcnt(0)
	v_cmp_ne_u32_e32 vcc, v0, v1
	s_orn2_b64 s[28:29], vcc, exec
	s_branch .LBB0_603
